# HGRN mode1 chunk tail: gate/onorm load pairs issued together after the RED barrier
# speedup vs baseline: 1.0111x; 1.0111x over previous
; __device__ __forceinline__ float bflo(unsigned u) { return __uint_as_float(u << 16); }
; __device__ __forceinline__ float bfhi(unsigned u) { return __uint_as_float(u & 0xffff0000u); }
; __device__ __forceinline__ float siluf_(float x) { return x * __builtin_amdgcn_rcpf(1.f + __expf(-x)); }
; __device__ __forceinline__ u32x2 pack4(f32x4 v) { u32x2 r; r.x = cvt_pk_bf16(v[0], v[1]); r.y = cvt_pk_bf16(v[2], v[3]); return r; }
; template <int MODE> __device__ __forceinline__ void hgrn_unit(LAS unsigned char* lds, const Params& P, int unit) {
;     ...
;             __syncthreads();
;             const float rs = rsqrtf((RED[w * 16 + l15] + RED[(w ^ 4) * 16 + l15]) * (1.f / 128.f) + EPS);
;             const size_t tt = (size_t)(t0 + 16 * nt + l15);
; #pragma unroll
;             for (int i = 0; i < 4; ++i) {
;                 const int v0 = 16 * (mt0 + i) + 4 * quad;
;                 const u32x2 gw = *(const u32x2*)(ZA + tt * 4096 + 3072 + h * 128 + v0);
;                 const f32x4 on = *(const f32x4*)(P.in[14] + v0);
;                 f32x4 y;
;                 y[0] = o[i][0] * rs * on[0] * siluf_(bflo(gw.x)); y[1] = o[i][1] * rs * on[1] * siluf_(bfhi(gw.x));
;                 y[2] = o[i][2] * rs * on[2] * siluf_(bflo(gw.y)); y[3] = o[i][3] * rs * on[3] * siluf_(bfhi(gw.y));
;                 *(u32x2*)(MIX + tt * 2048 + h * 128 + v0) = pack4(y);
.LBB0_261:
	s_or_b64 exec, exec, s[0:1]
	v_add_u32_e32 v66, s11, v83
	s_waitcnt lgkmcnt(0)
	v_ashrrev_i32_e32 v67, 31, v66
	v_lshlrev_b64 v[106:107], 13, v[66:67]
	v_lshl_add_u64 v[106:107], s[72:73], 0, v[106:107]
	v_lshl_add_u64 v[106:107], v[106:107], 0, s[22:23]
	s_mov_b64 s[0:1], 0x1800
	v_lshl_add_u64 v[110:111], v[106:107], 0, s[0:1]
	v_lshl_add_u64 v[106:107], v[110:111], 0, v[58:59]
	s_barrier
	global_load_dwordx2 v[156:157], v[106:107], off
	global_load_dwordx4 v[164:167], v[50:51], off
	v_lshl_add_u64 v[182:183], v[110:111], 0, v[60:61]
	global_load_dwordx2 v[158:159], v[182:183], off
	global_load_dwordx4 v[168:171], v[52:53], off
	v_lshl_add_u64 v[182:183], v[110:111], 0, v[62:63]
	global_load_dwordx2 v[160:161], v[182:183], off
	global_load_dwordx4 v[172:175], v[54:55], off
	v_lshl_add_u64 v[182:183], v[110:111], 0, v[64:65]
	global_load_dwordx2 v[162:163], v[182:183], off
	global_load_dwordx4 v[176:179], v[56:57], off
	ds_read_b32 v114, v78
	ds_read_b32 v115, v79
	v_lshlrev_b64 v[66:67], 12, v[66:67]
	v_lshl_add_u64 v[66:67], s[12:13], 0, v[66:67]
	v_lshl_add_u64 v[116:117], v[110:111], 0, v[60:61]
	s_waitcnt lgkmcnt(0)
	v_add_f32_e32 v114, v114, v115
	v_fmamk_f32 v114, v114, 0x3c000000, v203
	v_mul_f32_e32 v115, 0x4b800000, v114
	v_cmp_gt_f32_e32 vcc, s71, v114
	s_waitcnt vmcnt(7)
	v_mov_b64_e32 v[112:113], v[156:157]
	v_lshlrev_b32_e32 v120, 16, v112
	v_cndmask_b32_e32 v114, v114, v115, vcc
	v_rsq_f32_e32 v118, v114
	v_and_b32_e32 v121, 0xffff0000, v112
	v_lshlrev_b32_e32 v112, 16, v113
	v_and_b32_e32 v113, 0xffff0000, v113
	v_mul_f32_e32 v119, 0x45800000, v118
	v_cndmask_b32_e32 v118, v118, v119, vcc
	v_pk_mul_f32 v[44:45], v[44:45], v[118:119] op_sel_hi:[1,0]
	v_pk_mul_f32 v[46:47], v[46:47], v[118:119] op_sel_hi:[1,0]
	v_mul_f32_e32 v119, 0xbfb8aa3b, v120
	v_mul_f32_e32 v122, 0xbfb8aa3b, v121
	v_mul_f32_e32 v123, 0xbfb8aa3b, v112
	v_mul_f32_e32 v124, 0xbfb8aa3b, v113
	v_exp_f32_e32 v119, v119
	v_exp_f32_e32 v122, v122
	v_exp_f32_e32 v123, v123
	v_exp_f32_e32 v124, v124
	v_add_f32_e32 v119, 1.0, v119
	v_add_f32_e32 v125, 1.0, v122
	v_add_f32_e32 v126, 1.0, v123
	v_add_f32_e32 v127, 1.0, v124
	v_rcp_f32_e32 v122, v119
	v_rcp_f32_e32 v123, v125
	v_rcp_f32_e32 v124, v126
	v_rcp_f32_e32 v125, v127
	s_waitcnt vmcnt(6)
	v_mov_b64_e32 v[106:107], v[164:165]
	v_mov_b64_e32 v[108:109], v[166:167]
	v_pk_mul_f32 v[44:45], v[106:107], v[44:45]
	v_pk_mul_f32 v[46:47], v[108:109], v[46:47]
	v_pk_mul_f32 v[106:107], v[122:123], v[120:121]
	v_pk_mul_f32 v[108:109], v[124:125], v[112:113]
	v_pk_mul_f32 v[44:45], v[106:107], v[44:45]
	v_pk_mul_f32 v[46:47], v[108:109], v[46:47]
	v_lshl_add_u64 v[114:115], v[66:67], 0, v[58:59]
	v_cvt_pk_bf16_f32 v44, v44, v45
	v_cvt_pk_bf16_f32 v45, v46, v47
	global_store_dwordx2 v[114:115], v[44:45], off
	s_nop 0
	v_pk_mul_f32 v[40:41], v[40:41], v[118:119] op_sel_hi:[1,0]
	v_pk_mul_f32 v[42:43], v[42:43], v[118:119] op_sel_hi:[1,0]
	v_lshl_add_u64 v[108:109], v[66:67], 0, v[60:61]
	v_lshl_add_u64 v[112:113], v[110:111], 0, v[62:63]
	s_and_b64 vcc, exec, s[64:65]
	s_waitcnt vmcnt(6)
	v_mov_b64_e32 v[106:107], v[158:159]
	v_lshlrev_b32_e32 v114, 16, v106
	v_and_b32_e32 v115, 0xffff0000, v106
	v_lshlrev_b32_e32 v106, 16, v107
	v_and_b32_e32 v107, 0xffff0000, v107
	v_mul_f32_e32 v116, 0xbfb8aa3b, v114
	v_mul_f32_e32 v117, 0xbfb8aa3b, v115
	v_mul_f32_e32 v119, 0xbfb8aa3b, v106
	v_mul_f32_e32 v120, 0xbfb8aa3b, v107
	v_exp_f32_e32 v116, v116
	v_exp_f32_e32 v117, v117
	v_exp_f32_e32 v119, v119
	v_exp_f32_e32 v120, v120
	v_add_f32_e32 v116, 1.0, v116
	v_add_f32_e32 v117, 1.0, v117
	v_add_f32_e32 v119, 1.0, v119
	v_add_f32_e32 v121, 1.0, v120
	v_rcp_f32_e32 v116, v116
	v_rcp_f32_e32 v117, v117
	v_rcp_f32_e32 v120, v119
	v_rcp_f32_e32 v121, v121
	s_waitcnt vmcnt(5)
	v_mov_b64_e32 v[44:45], v[168:169]
	v_mov_b64_e32 v[46:47], v[170:171]
	v_pk_mul_f32 v[40:41], v[44:45], v[40:41]
	v_pk_mul_f32 v[42:43], v[46:47], v[42:43]
	v_pk_mul_f32 v[44:45], v[116:117], v[114:115]
	v_pk_mul_f32 v[46:47], v[120:121], v[106:107]
	v_pk_mul_f32 v[40:41], v[40:41], v[44:45]
	v_pk_mul_f32 v[42:43], v[42:43], v[46:47]
	v_cvt_pk_bf16_f32 v40, v40, v41
	v_cvt_pk_bf16_f32 v41, v42, v43
	global_store_dwordx2 v[108:109], v[40:41], off
	s_nop 0
	v_lshl_add_u64 v[106:107], v[110:111], 0, v[64:65]
	v_pk_mul_f32 v[36:37], v[36:37], v[118:119] op_sel_hi:[1,0]
	v_pk_mul_f32 v[38:39], v[38:39], v[118:119] op_sel_hi:[1,0]
	v_lshl_add_u64 v[46:47], v[66:67], 0, v[62:63]
	v_pk_mul_f32 v[32:33], v[32:33], v[118:119] op_sel_hi:[1,0]
	v_pk_mul_f32 v[34:35], v[34:35], v[118:119] op_sel_hi:[1,0]
	s_waitcnt vmcnt(5)
	v_mov_b64_e32 v[44:45], v[160:161]
	v_lshlrev_b32_e32 v108, 16, v44
	v_and_b32_e32 v109, 0xffff0000, v44
	v_lshlrev_b32_e32 v44, 16, v45
	v_and_b32_e32 v45, 0xffff0000, v45
	v_mul_f32_e32 v110, 0xbfb8aa3b, v108
	v_mul_f32_e32 v111, 0xbfb8aa3b, v109
	v_mul_f32_e32 v112, 0xbfb8aa3b, v44
	v_mul_f32_e32 v113, 0xbfb8aa3b, v45
	v_exp_f32_e32 v110, v110
	v_exp_f32_e32 v111, v111
	v_exp_f32_e32 v112, v112
	v_exp_f32_e32 v113, v113
	v_add_f32_e32 v110, 1.0, v110
	v_add_f32_e32 v111, 1.0, v111
	v_add_f32_e32 v112, 1.0, v112
	v_add_f32_e32 v113, 1.0, v113
	v_rcp_f32_e32 v110, v110
	v_rcp_f32_e32 v111, v111
	v_rcp_f32_e32 v112, v112
	v_rcp_f32_e32 v113, v113
	s_waitcnt vmcnt(4)
	v_mov_b64_e32 v[40:41], v[172:173]
	v_mov_b64_e32 v[42:43], v[174:175]
	v_pk_mul_f32 v[36:37], v[36:37], v[40:41]
	v_pk_mul_f32 v[38:39], v[38:39], v[42:43]
	v_pk_mul_f32 v[40:41], v[110:111], v[108:109]
	v_pk_mul_f32 v[42:43], v[112:113], v[44:45]
	v_pk_mul_f32 v[36:37], v[36:37], v[40:41]
	v_pk_mul_f32 v[38:39], v[38:39], v[42:43]
	v_cvt_pk_bf16_f32 v36, v36, v37
	v_cvt_pk_bf16_f32 v37, v38, v39
	global_store_dwordx2 v[46:47], v[36:37], off
	s_nop 0
	v_lshl_add_u64 v[42:43], v[66:67], 0, v[64:65]
	s_waitcnt vmcnt(4)
	v_mov_b64_e32 v[40:41], v[162:163]
	v_lshlrev_b32_e32 v44, 16, v40
	v_and_b32_e32 v45, 0xffff0000, v40
	v_lshlrev_b32_e32 v40, 16, v41
	v_and_b32_e32 v41, 0xffff0000, v41
	v_mul_f32_e32 v46, 0xbfb8aa3b, v44
	v_mul_f32_e32 v47, 0xbfb8aa3b, v45
	v_mul_f32_e32 v66, 0xbfb8aa3b, v40
	v_mul_f32_e32 v67, 0xbfb8aa3b, v41
	v_exp_f32_e32 v46, v46
	v_exp_f32_e32 v47, v47
	v_exp_f32_e32 v66, v66
	v_exp_f32_e32 v67, v67
	v_add_f32_e32 v46, 1.0, v46
	v_add_f32_e32 v47, 1.0, v47
	v_add_f32_e32 v66, 1.0, v66
	v_add_f32_e32 v67, 1.0, v67
	v_rcp_f32_e32 v46, v46
	v_rcp_f32_e32 v47, v47
	v_rcp_f32_e32 v66, v66
	v_rcp_f32_e32 v67, v67
	s_waitcnt vmcnt(3)
	v_mov_b64_e32 v[36:37], v[176:177]
	v_mov_b64_e32 v[38:39], v[178:179]
	v_pk_mul_f32 v[32:33], v[32:33], v[36:37]
	v_pk_mul_f32 v[34:35], v[34:35], v[38:39]
	v_pk_mul_f32 v[36:37], v[46:47], v[44:45]
	v_pk_mul_f32 v[38:39], v[66:67], v[40:41]
	v_pk_mul_f32 v[32:33], v[32:33], v[36:37]
	v_pk_mul_f32 v[34:35], v[34:35], v[38:39]
	v_cvt_pk_bf16_f32 v32, v32, v33
	v_cvt_pk_bf16_f32 v33, v34, v35
	global_store_dwordx2 v[42:43], v[32:33], off
	s_cbranch_vccnz .LBB0_263
; __device__ __forceinline__ f32x4 mfma16(bf16x8 a, bf16x8 b, f32x4 c) { return __builtin_amdgcn_mfma_f32_16x16x32_bf16(a, b, c, 0, 0, 0); }
; template <int MODE> __device__ __forceinline__ void hgrn_unit(LAS unsigned char* lds, const Params& P, int unit) {
;     ...
;         if (MODE == 0 || c < 3) {
;             float dl[4];
; #pragma unroll
;             for (int r = 0; r < 4; ++r) dl[r] = DL[16 * w + 4 * quad + r];
; #pragma unroll
;             for (int nt = 0; nt < 8; ++nt)
; #pragma unroll
;                 for (int r = 0; r < 4; ++r) S[nt][r] *= dl[r];
;             {
;                 bf16x8 fk[2], fvv[2][8];
; #pragma unroll
;                 for (int ks = 0; ks < 2; ++ks) { fk[ks] = trfrag(T2, TS, 32 * ks, 16 * w, lane);
; #pragma unroll
;                     for (int nt = 0; nt < 8; ++nt) fvv[ks][nt] = trfrag(T3, TS, 32 * ks, 16 * nt, lane); }
;                 __builtin_amdgcn_sched_barrier(0);
; #pragma unroll
;                 for (int ks = 0; ks < 2; ++ks)
; #pragma unroll
;                     for (int nt = 0; nt < 8; ++nt) S[nt] = mfma16(fk[ks], fvv[ks][nt], S[nt]);
;             }
	ds_read_b128 v[32:35], v81
	s_waitcnt lgkmcnt(0)
	v_pk_mul_f32 v[2:3], v[2:3], v[34:35]
	v_pk_mul_f32 v[0:1], v[0:1], v[32:33]
	v_pk_mul_f32 v[6:7], v[6:7], v[34:35]
	v_pk_mul_f32 v[4:5], v[4:5], v[32:33]
	v_pk_mul_f32 v[10:11], v[10:11], v[34:35]
	v_pk_mul_f32 v[8:9], v[8:9], v[32:33]
	v_pk_mul_f32 v[14:15], v[14:15], v[34:35]
	v_pk_mul_f32 v[12:13], v[12:13], v[32:33]
	v_pk_mul_f32 v[18:19], v[18:19], v[34:35]
	v_pk_mul_f32 v[16:17], v[16:17], v[32:33]
	v_pk_mul_f32 v[22:23], v[22:23], v[34:35]
	v_pk_mul_f32 v[20:21], v[20:21], v[32:33]
	v_pk_mul_f32 v[26:27], v[26:27], v[34:35]
	v_pk_mul_f32 v[24:25], v[24:25], v[32:33]
	v_pk_mul_f32 v[30:31], v[30:31], v[34:35]
	v_pk_mul_f32 v[28:29], v[28:29], v[32:33]
	ds_read_b64_tr_b16 v[32:33], v101 offset:18432
	ds_read_b64_tr_b16 v[34:35], v101 offset:19584
	ds_read_b64_tr_b16 v[38:39], v102 offset:38016
	ds_read_b64_tr_b16 v[36:37], v102 offset:36864
	ds_read_b64_tr_b16 v[40:41], v102 offset:36896
	ds_read_b64_tr_b16 v[42:43], v102 offset:38048
	ds_read_b64_tr_b16 v[44:45], v102 offset:36928
	ds_read_b64_tr_b16 v[46:47], v102 offset:38080
	ds_read_b64_tr_b16 v[106:107], v102 offset:36960
	ds_read_b64_tr_b16 v[108:109], v102 offset:38112
	ds_read_b64_tr_b16 v[110:111], v102 offset:36992
	ds_read_b64_tr_b16 v[112:113], v102 offset:38144
	ds_read_b64_tr_b16 v[114:115], v102 offset:37024
	ds_read_b64_tr_b16 v[116:117], v102 offset:38176
	ds_read_b64_tr_b16 v[118:119], v102 offset:37056
	ds_read_b64_tr_b16 v[120:121], v102 offset:38208
	ds_read_b64_tr_b16 v[122:123], v102 offset:37088
	ds_read_b64_tr_b16 v[124:125], v102 offset:38240
	ds_read_b64_tr_b16 v[126:127], v101 offset:27648
	ds_read_b64_tr_b16 v[128:129], v101 offset:28800
	ds_read_b64_tr_b16 v[130:131], v102 offset:46080
	ds_read_b64_tr_b16 v[132:133], v102 offset:47232
	ds_read_b64_tr_b16 v[134:135], v102 offset:46112
	ds_read_b64_tr_b16 v[136:137], v102 offset:47264
	ds_read_b64_tr_b16 v[138:139], v102 offset:46144
	ds_read_b64_tr_b16 v[140:141], v102 offset:47296
	ds_read_b64_tr_b16 v[142:143], v102 offset:46176
	ds_read_b64_tr_b16 v[144:145], v102 offset:47328
	ds_read_b64_tr_b16 v[146:147], v102 offset:46208
	ds_read_b64_tr_b16 v[148:149], v102 offset:47360
	ds_read_b64_tr_b16 v[150:151], v102 offset:46240
	ds_read_b64_tr_b16 v[152:153], v102 offset:47392
	ds_read_b64_tr_b16 v[154:155], v102 offset:46272
	ds_read_b64_tr_b16 v[156:157], v102 offset:47424
	ds_read_b64_tr_b16 v[158:159], v102 offset:46304
	ds_read_b64_tr_b16 v[160:161], v102 offset:47456
	s_waitcnt lgkmcnt(14)
	v_mfma_f32_16x16x32_bf16 v[0:3], v[32:35], v[36:39], v[0:3]
	v_mfma_f32_16x16x32_bf16 v[4:7], v[32:35], v[40:43], v[4:7]
	v_mfma_f32_16x16x32_bf16 v[8:11], v[32:35], v[44:47], v[8:11]
	v_mfma_f32_16x16x32_bf16 v[12:15], v[32:35], v[106:109], v[12:15]
	v_mfma_f32_16x16x32_bf16 v[16:19], v[32:35], v[110:113], v[16:19]
	v_mfma_f32_16x16x32_bf16 v[20:23], v[32:35], v[114:117], v[20:23]
	v_mfma_f32_16x16x32_bf16 v[24:27], v[32:35], v[118:121], v[24:27]
	v_mfma_f32_16x16x32_bf16 v[28:31], v[32:35], v[122:125], v[28:31]
	v_mfma_f32_16x16x32_bf16 v[0:3], v[126:129], v[130:133], v[0:3]
	s_waitcnt lgkmcnt(12)
	v_mfma_f32_16x16x32_bf16 v[4:7], v[126:129], v[134:137], v[4:7]
	s_waitcnt lgkmcnt(10)
	v_mfma_f32_16x16x32_bf16 v[8:11], v[126:129], v[138:141], v[8:11]
	s_waitcnt lgkmcnt(8)
	v_mfma_f32_16x16x32_bf16 v[12:15], v[126:129], v[142:145], v[12:15]
	s_waitcnt lgkmcnt(6)
	v_mfma_f32_16x16x32_bf16 v[16:19], v[126:129], v[146:149], v[16:19]
	s_waitcnt lgkmcnt(4)
	v_mfma_f32_16x16x32_bf16 v[20:23], v[126:129], v[150:153], v[20:23]
	s_waitcnt lgkmcnt(2)
	v_mfma_f32_16x16x32_bf16 v[24:27], v[126:129], v[154:157], v[24:27]
	s_waitcnt lgkmcnt(0)
	v_mfma_f32_16x16x32_bf16 v[28:31], v[126:129], v[158:161], v[28:31]
